# summary strip head: window-row addresses stepped by the row stride (one 64-bit multiply-add instead of eleven, ten index adds gone)
# baseline (speedup 1.0000x reference)
.LBB0_391:
	v_readlane_b32 s4, v252, 0
	v_readlane_b32 s5, v252, 1
	s_waitcnt lgkmcnt(0)
	s_barrier
	s_load_dwordx4 s[44:47], s[4:5], 0x40
	s_nop 0
	s_load_dwordx2 s[4:5], s[4:5], 0xc8
	v_readlane_b32 s6, v252, 4
	v_mbcnt_lo_u32_b32 v0, -1, 0
	v_mbcnt_hi_u32_b32 v0, -1, v0
	v_readlane_b32 s28, v253, 41
	v_readlane_b32 s29, v253, 42
	s_waitcnt lgkmcnt(0)
	s_add_u32 s24, s4, 0x200000
	s_addc_u32 s25, s5, 0
	s_add_u32 s26, s4, 0x4200000
	s_addc_u32 s27, s5, 0
	s_add_u32 s33, s4, 0xf600000
	s_addc_u32 s36, s5, 0
	s_add_u32 s22, s4, 0x180000
	v_or_b32_e32 v180, s6, v0
	s_addc_u32 s23, s5, 0
	s_add_u32 s6, s4, 0x188000
	v_and_b32_e32 v181, 63, v180
	v_ashrrev_i32_e32 v0, 6, v180
	v_and_b32_e32 v185, 15, v180
	v_and_b32_e32 v1, 3, v180
	v_lshlrev_b32_e32 v2, 2, v180
	v_readfirstlane_b32 s37, v0
	s_addc_u32 s7, s5, 0
	s_andn2_b64 vcc, exec, s[28:29]
	v_and_b32_e32 v183, 48, v180
	v_cmp_gt_u32_e64 s[40:41], 16, v181
	v_and_or_b32 v184, v2, 48, v1
	v_lshlrev_b32_e32 v182, 2, v185
	s_cbranch_vccnz .LBB0_432
	s_lshl_b32 s28, s56, 5
	s_add_i32 s28, s37, s28
	v_and_b32_e32 v148, 48, v181
	s_lshl_b32 s34, s56, 2
	s_ashr_i32 s29, s28, 31
	v_lshl_add_u64 v[2:3], s[24:25], 0, v[148:149]
	s_lshl_b64 s[28:29], s[28:29], 13
	s_or_b32 s34, s34, 1
	v_lshl_add_u64 v[4:5], v[2:3], 0, s[28:29]
	s_lshl_b32 s28, s34, 3
	s_add_i32 s28, s37, s28
	s_ashr_i32 s29, s28, 31
	s_lshl_b32 s30, s37, 6
	v_lshlrev_b32_e32 v148, 7, v185
	s_lshl_b64 s[28:29], s[28:29], 13
	v_or_b32_e32 v186, s30, v185
	v_lshl_add_u64 v[132:133], v[4:5], 0, v[148:149]
	v_lshl_add_u64 v[4:5], v[2:3], 0, s[28:29]
	s_lshl_b32 s96, s56, 11
	s_lshl_b32 s31, s56, 1
	v_lshl_add_u64 v[134:135], v[4:5], 0, v[148:149]
	v_add_u32_e32 v4, s96, v186
	v_ashrrev_i32_e32 v5, 31, v4
	s_lshl_b32 s28, s56, 10
	s_or_b32 s31, s31, 1
	v_lshl_add_u64 v[136:137], v[4:5], 2, s[22:23]
	v_subrev_u32_e32 v4, s28, v4
	s_lshl_b32 s28, s31, 4
	s_add_i32 s28, s37, s28
	v_lshl_add_u32 v6, s34, 9, v186
	s_lshl_b32 s34, s31, 1
	s_ashr_i32 s29, s28, 31
	v_ashrrev_i32_e32 v5, 31, v4
	s_lshl_b64 s[28:29], s[28:29], 13
	s_or_b32 s34, s34, 1
	v_lshl_add_u64 v[140:141], v[4:5], 2, s[6:7]
	v_lshl_add_u64 v[4:5], v[2:3], 0, s[28:29]
	s_lshl_b32 s28, s34, 3
	s_add_i32 s28, s37, s28
	s_ashr_i32 s29, s28, 31
	s_lshl_b64 s[28:29], s[28:29], 13
	v_lshl_add_u64 v[2:3], v[2:3], 0, s[28:29]
	v_lshl_add_u64 v[144:145], v[2:3], 0, v[148:149]
	v_lshl_add_u32 v2, s31, 10, v186
	v_ashrrev_i32_e32 v3, 31, v2
	s_lshl_b32 s28, s31, 9
	v_lshl_add_u64 v[146:147], v[2:3], 2, s[22:23]
	v_subrev_u32_e32 v2, s28, v2
	v_lshl_add_u64 v[142:143], v[4:5], 0, v[148:149]
	v_lshl_add_u32 v4, s34, 9, v186
	v_ashrrev_i32_e32 v3, 31, v2
	v_ashrrev_i32_e32 v5, 31, v4
	v_lshl_add_u64 v[158:159], v[2:3], 2, s[6:7]
	v_lshlrev_b32_e32 v2, 5, v181
	v_mov_b32_e32 v3, v149
	v_lshl_add_u64 v[156:157], v[4:5], 2, s[22:23]
	v_lshl_add_u64 v[4:5], s[44:45], 0, v[2:3]
	v_lshl_add_u64 v[160:161], s[96:97], 2, v[4:5]
	s_lshl_b32 s96, s56, 9
	s_lshl_b64 s[28:29], s[96:97], 2
	s_add_u32 s28, s46, s28
	s_addc_u32 s29, s47, s29
	v_lshl_add_u64 v[166:167], s[28:29], 0, v[2:3]
	s_movk_i32 s28, 0x2080
	v_mul_lo_u32 v5, v0, s28
	s_lshl_b32 s28, s37, 7
	v_ashrrev_i32_e32 v7, 31, v6
	s_add_i32 s28, s28, 0
	v_lshrrev_b32_e32 v1, 4, v181
	v_lshl_add_u64 v[138:139], v[6:7], 2, s[22:23]
	v_add_u32_e32 v6, s28, v183
	s_movk_i32 s28, 0x4100
	v_mad_u32_u24 v189, v1, s28, 0
	v_readlane_b32 s28, v254, 33
	s_add_i32 s28, s37, s28
	s_ashr_i32 s29, s28, 31
	s_lshl_b64 s[28:29], s[28:29], 13
	v_lshlrev_b32_e32 v187, 3, v0
	v_or3_b32 v0, s28, v148, v183
	v_readlane_b32 s28, v254, 20
	s_add_i32 s28, s37, s28
	v_mov_b32_e32 v1, s29
	s_ashr_i32 s29, s28, 31
	s_lshl_b64 s[28:29], s[28:29], 13
	v_lshl_add_u64 v[170:171], s[4:5], 0, v[0:1]
	v_or3_b32 v0, s28, v148, v183
	v_readlane_b32 s28, v252, 62
	s_add_i32 s28, s37, s28
	v_mov_b32_e32 v1, s29
	s_ashr_i32 s29, s28, 31
	s_lshl_b64 s[28:29], s[28:29], 13
	v_lshl_add_u64 v[172:173], s[4:5], 0, v[0:1]
	v_or3_b32 v0, s28, v148, v183
	v_readlane_b32 s28, v254, 42
	s_add_i32 s28, s37, s28
	v_mov_b32_e32 v1, s29
	s_ashr_i32 s29, s28, 31
	s_lshl_b64 s[28:29], s[28:29], 13
	v_lshl_add_u64 v[174:175], s[4:5], 0, v[0:1]
	v_or3_b32 v0, s28, v148, v183
	v_readlane_b32 s28, v254, 41
	s_add_i32 s28, s28, s30
	s_mul_i32 s34, s37, 0x7000
	v_add_u32_e32 v193, s28, v185
	v_readlane_b32 s28, v254, 40
	s_add_i32 s28, s28, s30
	s_mul_hi_i32 s31, s37, 0x7000
	v_add_u32_e32 v194, s28, v185
	s_add_u32 s28, s4, s34
	v_lshlrev_b32_e32 v2, 4, v181
	v_mov_b32_e32 v1, s29
	s_addc_u32 s29, s5, s31
	v_add_u32_e32 v4, 0, v2
	v_mul_u32_u24_e32 v7, 0x410, v184
	v_lshl_add_u64 v[176:177], s[4:5], 0, v[0:1]
	v_add_co_u32_e32 v242, vcc, s2, v176
	s_nop 1
	v_addc_co_u32_e32 v243, vcc, 0, v177, vcc
	v_add_co_u32_e32 v244, vcc, s2, v174
	s_nop 1
	v_addc_co_u32_e32 v245, vcc, 0, v175, vcc
	v_add_co_u32_e32 v246, vcc, s2, v172
	s_nop 1
	v_addc_co_u32_e32 v247, vcc, 0, v173, vcc
	v_add_co_u32_e32 v248, vcc, s2, v170
	s_nop 1
	v_addc_co_u32_e32 v249, vcc, 0, v171, vcc
	v_mov_b32_e32 v174, s3
	v_mov_b32_e32 v175, 0
	v_lshl_add_u64 v[0:1], s[28:29], 0, v[2:3]
	s_mov_b64 s[28:29], 0xb700000
	v_lshl_add_u64 v[162:163], v[160:161], 0, s[14:15]
	v_lshl_add_u64 v[164:165], v[160:161], 0, s[16:17]
	v_lshl_add_u64 v[168:169], s[26:27], 0, v[2:3]
	v_add_u32_e32 v188, -2, v187
	v_or_b32_e32 v190, 64, v182
	v_or_b32_e32 v191, 0x80, v182
	v_or_b32_e32 v192, 0xc0, v182
	v_lshl_add_u64 v[178:179], v[0:1], 0, s[28:29]
	v_add_u32_e32 v195, v4, v5
	v_add_u32_e32 v196, v6, v7
	s_mov_b32 s38, s95
	s_branch .LBB0_394

.LBB0_402:
	global_load_dwordx4 v[108:111], v[132:133], off
	global_load_dwordx4 v[92:95], v[132:133], off offset:64
	global_load_dwordx4 v[100:103], v[134:135], off
	global_load_dwordx4 v[88:91], v[134:135], off offset:64
	global_load_dword v104, v[136:137], off
	global_load_dword v96, v[138:139], off
	global_load_dword v6, v[140:141], off
	global_load_dwordx4 v[20:23], v[142:143], off
	global_load_dwordx4 v[8:11], v[144:145], off
	global_load_dwordx4 v[12:15], v[142:143], off offset:64
	global_load_dwordx4 v[0:3], v[144:145], off offset:64
	global_load_dword v16, v[146:147], off
	global_load_dword v4, v[156:157], off
	global_load_dword v148, v[158:159], off
	global_load_dwordx4 v[28:31], v[160:161], off offset:16
	global_load_dwordx4 v[48:51], v[160:161], off
	global_load_dwordx4 v[32:35], v[160:161], off offset:2064
	global_load_dwordx4 v[52:55], v[160:161], off offset:2048
	global_load_dwordx4 v[36:39], v[162:163], off offset:16
	global_load_dwordx4 v[56:59], v[162:163], off
	global_load_dwordx4 v[24:27], v[164:165], off offset:16
	global_load_dwordx4 v[44:47], v[164:165], off
	global_load_dwordx4 v[40:43], v[166:167], off offset:16
	global_load_dwordx4 v[60:63], v[166:167], off
	s_add_i32 s34, s42, 0xffffff00
	s_and_b64 s[28:29], s[28:29], exec
	s_cselect_b32 s28, s42, s34
	v_add_u32_e32 v7, s28, v187
	v_cmp_lt_i32_e32 vcc, 1, v7
	v_cmp_ge_u32_e64 s[42:43], s31, v7
	v_add_u32_e32 v5, s39, v188
	s_and_b64 s[34:35], vcc, s[42:43]
	v_mov_b32_e32 v68, 0
	v_mov_b32_e32 v69, 0
	v_mov_b32_e32 v70, 0
	v_mov_b32_e32 v71, 0
	v_mov_b32_e32 v72, 0
	v_mad_i64_i32 v[18:19], vcc, v5, s3, v[168:169]
	s_and_saveexec_b64 s[28:29], s[34:35]
	s_cbranch_execz .LBB0_404
	global_load_dwordx4 v[68:71], v[18:19], off
.LBB0_404:
	s_or_b64 exec, exec, s[28:29]
	v_lshl_add_u64 v[18:19], v[18:19], 0, v[174:175]
	v_cmp_lt_i32_e32 vcc, 0, v7
	v_cmp_ge_i32_e64 s[42:43], s31, v7
	s_and_b64 s[34:35], vcc, s[42:43]
	v_mov_b32_e32 v73, 0
	v_mov_b32_e32 v74, 0
	v_mov_b32_e32 v75, 0
	s_and_saveexec_b64 s[28:29], s[34:35]
	s_cbranch_execz .LBB0_406
	global_load_dwordx4 v[72:75], v[18:19], off
.LBB0_406:
	s_or_b64 exec, exec, s[28:29]
	v_lshl_add_u64 v[18:19], v[18:19], 0, v[174:175]
	v_cmp_gt_u32_e32 vcc, s31, v7
	v_mov_b32_e32 v116, 0
	v_mov_b32_e32 v124, 0
	v_mov_b32_e32 v125, 0
	v_mov_b32_e32 v126, 0
	v_mov_b32_e32 v127, 0
	s_and_saveexec_b64 s[28:29], vcc
	s_cbranch_execz .LBB0_408
	global_load_dwordx4 v[124:127], v[18:19], off
.LBB0_408:
	s_or_b64 exec, exec, s[28:29]
	v_lshl_add_u64 v[18:19], v[18:19], 0, v[174:175]
	v_or_b32_e32 v17, 1, v7
	v_cmp_lt_i32_e32 vcc, -2, v7
	v_cmp_gt_u32_e64 s[42:43], s31, v17
	s_and_b64 s[34:35], vcc, s[42:43]
	v_mov_b32_e32 v117, 0
	v_mov_b32_e32 v118, 0
	v_mov_b32_e32 v119, 0
	s_and_saveexec_b64 s[28:29], s[34:35]
	s_cbranch_execz .LBB0_410
	global_load_dwordx4 v[116:119], v[18:19], off
.LBB0_410:
	s_or_b64 exec, exec, s[28:29]
	v_lshl_add_u64 v[18:19], v[18:19], 0, v[174:175]
	v_or_b32_e32 v17, 2, v7
	v_cmp_lt_i32_e32 vcc, -3, v7
	v_cmp_gt_u32_e64 s[42:43], s31, v17
	s_and_b64 s[34:35], vcc, s[42:43]
	v_mov_b32_e32 v84, 0
	v_mov_b32_e32 v128, 0
	v_mov_b32_e32 v129, 0
	v_mov_b32_e32 v130, 0
	v_mov_b32_e32 v131, 0
	s_and_saveexec_b64 s[28:29], s[34:35]
	s_cbranch_execz .LBB0_412
	global_load_dwordx4 v[128:131], v[18:19], off
.LBB0_412:
	s_or_b64 exec, exec, s[28:29]
	v_lshl_add_u64 v[18:19], v[18:19], 0, v[174:175]
	v_or_b32_e32 v17, 3, v7
	v_cmp_lt_i32_e32 vcc, -4, v7
	v_cmp_gt_u32_e64 s[42:43], s31, v17
	s_and_b64 s[34:35], vcc, s[42:43]
	v_mov_b32_e32 v85, 0
	v_mov_b32_e32 v86, 0
	v_mov_b32_e32 v87, 0
	s_and_saveexec_b64 s[28:29], s[34:35]
	s_cbranch_execz .LBB0_414
	global_load_dwordx4 v[84:87], v[18:19], off
.LBB0_414:
	s_or_b64 exec, exec, s[28:29]
	v_lshl_add_u64 v[18:19], v[18:19], 0, v[174:175]
	v_or_b32_e32 v17, 4, v7
	v_cmp_lt_i32_e32 vcc, -5, v7
	v_cmp_gt_u32_e64 s[42:43], s31, v17
	s_and_b64 s[34:35], vcc, s[42:43]
	v_mov_b32_e32 v76, 0
	v_mov_b32_e32 v120, 0
	v_mov_b32_e32 v121, 0
	v_mov_b32_e32 v122, 0
	v_mov_b32_e32 v123, 0
	s_and_saveexec_b64 s[28:29], s[34:35]
	s_cbranch_execz .LBB0_416
	global_load_dwordx4 v[120:123], v[18:19], off
.LBB0_416:
	s_or_b64 exec, exec, s[28:29]
	v_lshl_add_u64 v[18:19], v[18:19], 0, v[174:175]
	v_or_b32_e32 v17, 5, v7
	v_cmp_lt_i32_e32 vcc, -6, v7
	v_cmp_gt_u32_e64 s[42:43], s31, v17
	s_and_b64 s[34:35], vcc, s[42:43]
	v_mov_b32_e32 v77, 0
	v_mov_b32_e32 v78, 0
	v_mov_b32_e32 v79, 0
	s_and_saveexec_b64 s[28:29], s[34:35]
	s_cbranch_execz .LBB0_418
	global_load_dwordx4 v[76:79], v[18:19], off
.LBB0_418:
	s_or_b64 exec, exec, s[28:29]
	v_lshl_add_u64 v[18:19], v[18:19], 0, v[174:175]
	v_or_b32_e32 v17, 6, v7
	v_cmp_lt_i32_e32 vcc, -7, v7
	v_cmp_gt_u32_e64 s[42:43], s31, v17
	s_and_b64 s[34:35], vcc, s[42:43]
	v_mov_b32_e32 v64, 0
	v_mov_b32_e32 v112, 0
	v_mov_b32_e32 v113, 0
	v_mov_b32_e32 v114, 0
	v_mov_b32_e32 v115, 0
	s_and_saveexec_b64 s[28:29], s[34:35]
	s_cbranch_execz .LBB0_420
	global_load_dwordx4 v[112:115], v[18:19], off
.LBB0_420:
	s_or_b64 exec, exec, s[28:29]
	v_lshl_add_u64 v[18:19], v[18:19], 0, v[174:175]
	v_or_b32_e32 v17, 7, v7
	v_cmp_lt_i32_e32 vcc, -8, v7
	v_cmp_gt_u32_e64 s[42:43], s31, v17
	s_and_b64 s[34:35], vcc, s[42:43]
	v_mov_b32_e32 v65, 0
	v_mov_b32_e32 v66, 0
	v_mov_b32_e32 v67, 0
	s_and_saveexec_b64 s[28:29], s[34:35]
	s_cbranch_execz .LBB0_422
	global_load_dwordx4 v[64:67], v[18:19], off
.LBB0_422:
	s_or_b64 exec, exec, s[28:29]
	v_lshl_add_u64 v[18:19], v[18:19], 0, v[174:175]
	v_cmp_lt_i32_e32 vcc, -9, v7
	v_add_u32_e32 v7, 8, v7
	v_cmp_gt_u32_e64 s[42:43], s31, v7
	s_and_b64 s[34:35], vcc, s[42:43]
	v_mov_b32_e32 v80, 0
	v_mov_b32_e32 v81, 0
	v_mov_b32_e32 v82, 0
	v_mov_b32_e32 v83, 0
	s_and_saveexec_b64 s[28:29], s[34:35]
	s_cbranch_execz .LBB0_424
	global_load_dwordx4 v[80:83], v[18:19], off
